# tremap: P0 weight-transpose items ordered k-block fastest (8 waves of a CU write 1 KiB contiguous per output row), on top of v41 set
# speedup vs baseline: 1.0021x; 1.0021x over previous
; template <bool MAPIN>
; __device__ __forceinline__ void transpose_item(const float* W, int K, int N, bf16_t* WT, LAS float* scr, int item, int lane, const float* gk = nullptr) {
;     const int nblk = N / 32, kb = item / nblk, nb = item % nblk, k0 = 64 * kb, n0 = 32 * nb;
; __device__ __forceinline__ void p0_prologue(const Params& p, LAS unsigned char* lds, int vcu_in, int G_in, int cu0, int part) {
;     ...
;             { const int k0 = 64 * (r / 64);
;               const float* gk = k0 < 1024 ? p.g_attn + l * 1024 : (k0 < 1536 ? p.g_conv + l * 512 - 1024 : p.g_mem + l * 512 - 1536);
;               transpose_item<false>(p.w_out + (size_t)l * 2048 * 2048, 2048, 2048, (bf16_t*)(ws + WS_WOUT) + (size_t)l * 2048 * 2048, scr, r, lane, gk); }
.LBB0_98:
	v_mul_hi_i32 v0, v36, s41
	v_add_u32_e32 v0, v0, v36
	v_lshrrev_b32_e32 v1, 31, v0
	v_ashrrev_i32_e32 v0, 12, v0
	v_add_u32_e32 v2, v0, v1
	v_mul_i32_i24_e32 v0, 0x1e00, v2
	v_sub_u32_e32 v6, v36, v0
	v_cmp_lt_i32_e32 vcc, s42, v6
	s_and_saveexec_b64 s[0:1], vcc
	s_xor_b64 s[0:1], exec, s[0:1]
	s_cbranch_execz .LBB0_118
	v_add_u32_e32 v7, 0xffffea00, v6
	v_and_b32_e32 v37, 0x7e0, v7
	v_and_b32_e32 v7, 31, v7
	v_lshlrev_b32_e32 v7, 6, v7
	v_cmp_lt_u32_e32 vcc, s43, v7
	s_and_saveexec_b64 s[16:17], vcc
	s_xor_b64 s[16:17], exec, s[16:17]
	s_cbranch_execz .LBB0_105
	v_lshlrev_b32_e32 v4, 9, v2
	v_cmp_lt_u32_e32 vcc, s44, v7
	v_ashrrev_i32_e32 v5, 31, v4
	s_and_saveexec_b64 s[18:19], vcc
	s_xor_b64 s[18:19], exec, s[18:19]
	v_lshl_add_u64 v[0:1], v[4:5], 2, s[92:93]
	v_lshl_add_u64 v[0:1], v[0:1], 0, s[12:13]
	s_andn2_saveexec_b64 s[18:19], s[18:19]
	v_lshl_add_u64 v[0:1], v[4:5], 2, s[90:91]
	v_lshl_add_u64 v[0:1], v[0:1], 0, s[14:15]
	s_or_b64 exec, exec, s[18:19]
.LBB0_105:
	s_andn2_saveexec_b64 s[16:17], s[16:17]
	v_lshlrev_b32_e32 v0, 10, v2
	v_ashrrev_i32_e32 v1, 31, v0
	v_lshl_add_u64 v[0:1], v[0:1], 2, s[88:89]
	s_or_b64 exec, exec, s[16:17]
	v_ashrrev_i32_e32 v3, 31, v2
	v_lshlrev_b32_e32 v4, 5, v6
	v_lshlrev_b64 v[10:11], 22, v[2:3]
	v_lshlrev_b64 v[2:3], 24, v[2:3]
	v_lshl_add_u64 v[2:3], s[94:95], 0, v[2:3]
	v_lshlrev_b32_e32 v14, 2, v37
	v_and_b32_e32 v24, 0xffc0, v7
	v_lshl_add_u64 v[2:3], v[2:3], 0, v[14:15]
	v_mov_b32_e32 v21, v15
	v_lshl_add_u64 v[2:3], v[2:3], 0, v[20:21]
	v_or_b32_e32 v5, v13, v24
	v_or_b32_e32 v4, v12, v24
	s_mov_b32 s16, 1
	s_mov_b32 s17, 0
	s_mov_b32 s18, 32

; template <bool MAPIN>
; __device__ __forceinline__ void transpose_item(const float* W, int K, int N, bf16_t* WT, LAS float* scr, int item, int lane, const float* gk = nullptr) {
;     const int nblk = N / 32, kb = item / nblk, nb = item % nblk, k0 = 64 * kb, n0 = 32 * nb;
; __device__ __forceinline__ void p0_prologue(const Params& p, LAS unsigned char* lds, int vcu_in, int G_in, int cu0, int part) {
;     ...
;             if (r < I_IN) { bf16_t* dst = l == 0 ? (bf16_t*)(dob + DO_WIN0) : (bf16_t*)(ws + WS_WIN1);
;                 transpose_item<true>(p.w_in + (size_t)l * 2048 * 5632, 2048, 5632, dst, scr, r, lane, l == 1 ? p.norm_in + 2048 : nullptr); continue; }
.LBB0_118:
	s_andn2_saveexec_b64 s[16:17], s[0:1]
	s_cbranch_execz .LBB0_97
	v_mov_b64_e32 v[0:1], s[62:63]
	v_mad_i64_i32 v[0:1], s[0:1], v2, s45, v[0:1]
	v_and_b32_e32 v2, 31, v6
	v_lshrrev_b32_e32 v37, 5, v6
	v_lshlrev_b32_e32 v10, 5, v37
	v_ashrrev_i32_e32 v11, 31, v10
	v_lshlrev_b32_sdwa v24, v33, sext(v2) dst_sel:DWORD dst_unused:UNUSED_PAD src0_sel:DWORD src1_sel:WORD_0
	v_lshl_add_u64 v[0:1], v[10:11], 2, v[0:1]
	v_mov_b32_e32 v21, v15
	v_lshl_add_u64 v[0:1], v[0:1], 0, v[20:21]
	v_mov_b32_e32 v3, v24
	s_mov_b32 s0, 1
	s_mov_b32 s1, 0
	s_mov_b32 s18, 32
